# EpiResid GEMM prologue touches the residual tile lines the epilogue reads (L2/MALL prefetch)
# baseline (speedup 1.0000x reference)
; #define PG8_STAGE(bufoff, gbase, voff) do { _Pragma("unroll") for (int _i = 0; _i < 2; ++_i) \
;         __builtin_amdgcn_global_load_lds((const unsigned*)((const char*)(gbase) + (voff)[_i]), (LAS unsigned*)(lds + (bufoff) + ldsw + _i * 8192), 16, 0, 0); } while (0)
; #define PG8_BAR __builtin_amdgcn_s_barrier()
; template <class Epi>
; __device__ __forceinline__ void gemm_phase(LAS unsigned char* lds, const Gemm g, const StaticOrder& S, const Epi& E, const int tid_in) {
;     ...
;     const char* cA = (const char*)g.A + (size_t)cur.pm * tstepA; const char* cB = (const char*)g.Bt + (size_t)cur.pn * tstepB;
;     PG8_STAGE(PG8_SB(0, 0), cB, voffB); PG8_STAGE(PG8_SB(0, 1), cB + hstepB, voffB); PG8_STAGE(PG8_SA(0, 0), cA, voffA); PG8_STAGE(PG8_SA(0, 1), cA + hstepA, voffA);
;     if (wr == 1) PG8_BAR;
;     PG8_WAIT_V(2); PG8_BAR;
;     PG8_STAGE(PG8_SB(1, 0), cB + kstep, voffB); PG8_STAGE(PG8_SA(1, 0), cA + kstep, voffA); PG8_STAGE(PG8_SB(1, 1), cB + hstepB + kstep, voffB);
;     PG8_WAIT_V(6); PG8_BAR;
;     template <int A0, int A1> __device__ __forceinline__ void run(const f32x4 (&acc)[2][2][4][2], const Unit& u, int wr, int wc, int fr, int fq) const {
;     ...
;         const float* xo = (u.pm < 64) ? xo_lat : xo_ctx - (size_t)ML * DM;
;         float* xn = (u.pm < 64) ? xn_lat : xn_ctx - (size_t)ML * DM;
;         const int row0 = u.pm * 256 + wr * 64 + fr;
;         float ssq[2][4];
; #pragma unroll
;         for (int ai = A0; ai < A1; ++ai)
; #pragma unroll
;             for (int m = 0; m < 4; ++m) ssq[ai][m] = 0.f;
; #pragma unroll
;         for (int bj = 0; bj < 2; ++bj) {
;             const int col = u.pn * 256 + bj * 128 + wc * 32 + fq * 8;
;             const f32x4 gv0 = *(const f32x4*)(gate + s * NMOD + col) * gmul, gv1 = *(const f32x4*)(gate + s * NMOD + col + 4) * gmul;
;             f32x4 wv0 = (f32x4){0.f, 0.f, 0.f, 0.f}, wv1 = wv0;
;             if (has_next) { wv0 = *(const f32x4*)(nw + col) * (*(const f32x4*)(nscale + s * NMOD + col) + 1.0f); wv1 = *(const f32x4*)(nw + col + 4) * (*(const f32x4*)(nscale + s * NMOD + col + 4) + 1.0f); }
; #pragma unroll
;             for (int ai = A0; ai < A1; ++ai)
; #pragma unroll
;                 for (int m = 0; m < 4; ++m) {
;                     const size_t off = (size_t)(row0 + ai * 128 + m * 16) * DM + col;
;                     const f32x4 x0 = *(const f32x4*)(xo + off) + gv0 * acc[ai][bj][m][0];
.LBB0_1220:
	s_add_i32 m0, s56, 0x18000
	v_lshl_add_u64 v[0:1], v[0:1], 0, s[54:55]
	s_waitcnt vmcnt(2)
	s_barrier
	global_load_lds_dwordx4 v[0:1], off
	v_lshl_add_u64 v[0:1], v[2:3], 0, s[54:55]
	s_add_i32 m0, s56, 0x1a000
	s_add_i32 s61, s56, 0x8000
	global_load_lds_dwordx4 v[0:1], off
	v_lshl_add_u64 v[0:1], v[8:9], 0, s[54:55]
	s_mov_b32 m0, s61
	s_add_i32 s62, s56, 0xa000
	global_load_lds_dwordx4 v[0:1], off
	v_lshl_add_u64 v[0:1], v[10:11], 0, s[54:55]
	s_mov_b32 m0, s62
	v_bfe_u32 v19, v12, 4, 2
	global_load_lds_dwordx4 v[0:1], off
	s_add_i32 m0, s56, 0x1c000
	v_lshl_add_u64 v[0:1], v[4:5], 0, s[54:55]
	global_load_lds_dwordx4 v[0:1], off
	v_lshl_add_u64 v[0:1], v[6:7], 0, s[54:55]
	s_add_i32 m0, s56, 0x1e000
	v_and_b32_e32 v12, 15, v12
	global_load_lds_dwordx4 v[0:1], off
	v_lshlrev_b32_e32 v21, 4, v19
	v_lshl_or_b32 v240, s5, 6, v12
	v_lshl_or_b32 v21, v12, 6, v21
	v_lshlrev_b32_e32 v12, 2, v12
	s_and_b32 s6, s4, 3
	s_lshr_b32 s60, s19, 6
	s_lshl_b32 s4, s5, 13
	v_and_b32_e32 v22, 32, v12
	v_bitop3_b32 v23, v21, s4, v22 bitop3:0xde
	s_lshl_b32 s4, s6, 12
	s_add_i32 s92, s60, -2
	v_lshlrev_b32_e32 v20, 3, v19
	s_cmpk_lt_u32 s8, 0x100
	s_cselect_b64 s[86:87], -1, 0
	v_lshl_or_b32 v242, s6, 5, v20
	s_ashr_i32 s94, s42, 31
	s_ashr_i32 s95, s26, 31
	s_lshl_b32 s6, s6, 2
	v_readlane_b32 s8, v255, 34
	v_lshlrev_b32_e32 v0, 6, v19
	s_movk_i32 s0, 0x80
	v_readlane_b32 s9, v255, 35
	s_add_u32 s96, s8, s6
	v_bitop3_b32 v243, v0, 64, v12 bitop3:0x36
	v_bitop3_b32 v244, v0, s0, v12 bitop3:0x36
	s_addc_u32 s97, s9, 0
	v_readlane_b32 s6, v255, 23
	v_add_u32_e32 v0, v15, v13
	v_readlane_b32 s7, v255, 24
	s_add_u32 s43, s6, 0xfc000000
	v_add_lshl_u32 v0, v0, v14, 1
	v_mov_b32_e32 v1, v129
	s_waitcnt vmcnt(6)
	s_addc_u32 s84, s7, -1
	v_lshl_add_u64 v[148:149], s[52:53], 0, v[0:1]
	v_add_u32_e32 v0, v18, v16
	v_cndmask_b32_e64 v144, 0.5, 1.0, s[76:77]
	s_add_u32 s85, s68, 0x1300000
	v_add_lshl_u32 v0, v0, v17, 1
	v_bitop3_b32 v241, v21, s4, v22 bitop3:0xde
	s_mov_b32 s93, 0
	v_cmp_eq_u32_e64 s[4:5], 0, v19
	s_addc_u32 s71, s69, 0
	v_mov_b32_e32 v146, v144
	v_mov_b32_e32 v147, v144
	v_lshl_add_u64 v[150:151], s[52:53], 0, v[0:1]
	v_add_u32_e32 v245, 0, v23
	s_barrier
	v_mbcnt_lo_u32_b32 v253, -1, 0
	v_mbcnt_hi_u32_b32 v253, -1, v253
	v_readlane_b32 s99, v255, 15
	v_lshrrev_b32_e32 v254, 3, v253
	v_and_b32_e32 v253, 7, v253
	v_lshlrev_b32_e32 v253, 7, v253
	v_lshl_add_u32 v251, v254, 12, v253
	s_lshl_b32 s98, s67, 20
	s_lshl_b32 s99, s99, 15
	s_add_u32 s98, s98, s99
	s_lshl_b32 s99, s63, 10
	s_add_u32 s98, s98, s99
	s_add_u32 s98, s98, s28
	s_addc_u32 s99, s29, 0
	global_load_dword v250, v251, s[98:99]
	s_add_u32 s98, s98, 0x40000
	s_addc_u32 s99, s99, 0
	global_load_dword v250, v251, s[98:99]
	s_add_u32 s98, s98, 0x40000
	s_addc_u32 s99, s99, 0
	global_load_dword v250, v251, s[98:99]
	s_add_u32 s98, s98, 0x40000
	s_addc_u32 s99, s99, 0
	global_load_dword v250, v251, s[98:99]
	s_branch .LBB0_1223
